# mix_nas rel-pos bias: 8 table reads per window tile preloaded unmasked ahead of the MFMAs instead of 8 serial exec-masked LDS round trips
# speedup vs baseline: 1.0011x; 1.0011x over previous
.LBB0_1064:
	s_bitcmp0_b32 s49, 0
	s_cselect_b32 s0, s37, s48
	s_add_i32 s0, s0, s36
	s_add_i32 s1, s0, 0xfffff200
	s_cmp_lt_u32 s1, 0xfffffa00
	s_cbranch_scc1 .LBB0_1063
	s_add_i32 s1, s0, 0xfffff800
	s_addk_i32 s0, 0xf500
	s_cmpk_lt_u32 s1, 0x300
	s_cselect_b32 s6, s1, s0
	s_lshr_b32 s0, s6, 7
	s_and_b32 s7, s6, 0x7f
	s_bfe_u32 s12, s6, 0x50002
	s_cmpk_gt_u32 s1, 0x2ff
	s_cselect_b64 s[26:27], -1, 0
	s_and_b64 s[2:3], s[26:27], exec
	s_movk_i32 s1, 0x1800
	s_cselect_b32 s1, s1, 0x1000
	s_lshl_b32 s2, s7, 4
	s_or_b32 s2, s2, s1
	v_or_b32_e32 v141, s2, v133
	s_lshl_b32 s2, s6, 4
	v_mov_b64_e32 v[2:3], s[10:11]
	s_and_b32 s7, s2, 48
	v_mad_u64_u32 v[2:3], s[2:3], v141, s33, v[2:3]
	s_and_b32 s44, s6, 0xffffff80
	s_mulk_i32 s1, 0x300
	s_add_u32 s2, s38, s1
	s_addc_u32 s3, s39, 0
	s_add_u32 s28, s2, s44
	s_addc_u32 s29, s3, 0
	s_add_u32 s1, s40, s1
	v_sub_u32_e64 v0, s12, 4 clamp
	s_addc_u32 s2, s41, 0
	s_lshl_b32 s3, s0, 18
	v_min_u32_e32 v66, 24, v0
	v_sub_u32_e64 v0, s7, 8 clamp
	s_add_u32 s30, s1, s3
	v_min_u32_e32 v93, 32, v0
	s_addc_u32 s31, s2, 0
	v_lshlrev_b32_e32 v0, 6, v66
	v_lshlrev_b32_e32 v142, 1, v136
	v_mov_b32_e32 v143, v1
	v_or_b32_e32 v150, v0, v93
	v_lshl_add_u64 v[12:13], s[30:31], 0, v[142:143]
	v_lshlrev_b32_e32 v146, 1, v138
	v_mov_b32_e32 v147, v1
	v_lshl_add_u64 v[2:3], v[2:3], 0, s[44:45]
	v_lshlrev_b32_e32 v144, 1, v132
	v_mov_b32_e32 v145, v1
	v_lshl_add_u64 v[14:15], v[12:13], 0, v[146:147]
	v_lshlrev_b32_e32 v0, 7, v150
	v_lshl_add_u64 v[2:3], v[2:3], 0, v[144:145]
	v_lshlrev_b32_e32 v148, 1, v134
	v_mov_b32_e32 v149, v1
	v_lshl_add_u64 v[12:13], v[14:15], 0, v[0:1]
	global_load_dwordx4 v[6:9], v[2:3], off
	s_nop 0
	global_load_dwordx4 v[2:5], v[2:3], off offset:16
	v_lshl_add_u64 v[10:11], s[28:29], 0, v[148:149]
	global_load_dwordx4 v[50:53], v[12:13], off
	global_load_dwordx4 v[62:65], v[12:13], off offset:256
	global_load_dwordx4 v[72:75], v[12:13], off offset:512
	global_load_dwordx4 v[42:45], v[12:13], off offset:768
	v_mul_lo_u32 v12, v150, s33
	v_lshl_add_u64 v[10:11], v[10:11], 0, v[144:145]
	v_add_u32_e32 v18, 0xc000, v12
	v_mov_b32_e32 v19, v1
	v_mov_b32_e32 v13, v1
	v_lshl_add_u64 v[18:19], v[10:11], 0, v[18:19]
	v_lshl_add_u64 v[20:21], v[10:11], 0, v[12:13]
	global_load_dwordx4 v[34:37], v[18:19], off
	global_load_dwordx4 v[30:33], v[18:19], off offset:16
	global_load_dwordx4 v[10:13], v[20:21], off offset:16
	global_load_dwordx4 v[76:79], v[20:21], off
	global_load_dwordx4 v[100:103], v[18:19], off offset:3072
	global_load_dwordx4 v[96:99], v[18:19], off offset:3088
	global_load_dwordx4 v[104:107], v[20:21], off offset:3088
	global_load_dwordx4 v[108:111], v[20:21], off offset:3072
	v_add_u32_e32 v16, 0x2000, v0
	v_mov_b32_e32 v17, v1
	v_lshl_add_u64 v[16:17], v[14:15], 0, v[16:17]
	s_mov_b64 s[2:3], 0xc000
	s_mov_b32 s1, 0xc000
	global_load_dwordx4 v[88:91], v[16:17], off
	global_load_dwordx4 v[84:87], v[16:17], off offset:256
	global_load_dwordx4 v[80:83], v[16:17], off offset:512
	global_load_dwordx4 v[68:71], v[16:17], off offset:768
	v_add_u32_e32 v0, 0x4000, v0
	v_lshl_add_u64 v[16:17], v[18:19], 0, s[2:3]
	v_add_co_u32_e32 v18, vcc, s1, v18
	v_lshl_add_u64 v[14:15], v[14:15], 0, v[0:1]
	s_nop 0
	v_addc_co_u32_e32 v19, vcc, 0, v19, vcc
	global_load_dwordx4 v[38:41], v[16:17], off offset:16
	global_load_dwordx4 v[46:49], v[16:17], off offset:3072
	global_load_dwordx4 v[58:61], v[18:19], off
	global_load_dwordx4 v[54:57], v[16:17], off offset:3088
	global_load_dwordx4 v[26:29], v[14:15], off
	global_load_dwordx4 v[22:25], v[14:15], off offset:256
	s_nop 0
	global_load_dwordx4 v[18:21], v[14:15], off offset:512
	s_nop 0
	global_load_dwordx4 v[14:17], v[14:15], off offset:768
	v_or_b32_e32 v67, s7, v133
	v_max_i32_e32 v0, 8, v67
	v_add_u32_e32 v0, -8, v0
	s_mul_i32 s1, s0, 0x744
	v_min_u32_e32 v92, 48, v0
	v_subrev_u32_e32 v0, s12, v66
	s_movk_i32 s2, 0x7c
	s_add_i32 s1, s1, 0
	v_mul_lo_u32 v0, v0, s2
	v_add_u32_e32 v94, v93, v135
	v_add_u32_e32 v93, 16, v92
	v_add_u32_e32 v0, s1, v0
	v_cmp_ge_u32_e32 vcc, v94, v92
	v_cmp_lt_u32_e64 s[6:7], v94, v93
	v_sub_u32_e32 v66, v94, v67
	v_add_u32_e32 v151, 0x18000, v0
	s_and_b64 s[12:13], vcc, s[6:7]
	v_mov_b32_e32 v0, 0xff800000
	v_med3_i32 v156, v66, -15, 15
	v_mov_b32_e32 v66, 0xff800000
	v_sub_u32_e32 v246, v94, v67
	v_or_b32_e32 v247, 1, v94
	v_sub_u32_e32 v247, v247, v67
	v_or_b32_e32 v248, 2, v94
	v_sub_u32_e32 v248, v248, v67
	v_or_b32_e32 v249, 3, v94
	v_sub_u32_e32 v249, v249, v67
	v_or_b32_e32 v250, 4, v94
	v_sub_u32_e32 v250, v250, v67
	v_or_b32_e32 v251, 5, v94
	v_sub_u32_e32 v251, v251, v67
	v_or_b32_e32 v252, 6, v94
	v_sub_u32_e32 v252, v252, v67
	v_or_b32_e32 v253, 7, v94
	v_sub_u32_e32 v253, v253, v67
	v_med3_i32 v246, v246, -15, 15
	v_med3_i32 v247, v247, -15, 15
	v_med3_i32 v248, v248, -15, 15
	v_med3_i32 v249, v249, -15, 15
	v_med3_i32 v250, v250, -15, 15
	v_med3_i32 v251, v251, -15, 15
	v_med3_i32 v252, v252, -15, 15
	v_med3_i32 v253, v253, -15, 15
	v_lshl_add_u32 v246, v246, 2, v151
	v_lshl_add_u32 v247, v247, 2, v151
	v_lshl_add_u32 v248, v248, 2, v151
	v_lshl_add_u32 v249, v249, 2, v151
	v_lshl_add_u32 v250, v250, 2, v151
	v_lshl_add_u32 v251, v251, 2, v151
	v_lshl_add_u32 v252, v252, 2, v151
	v_lshl_add_u32 v253, v253, 2, v151
	ds_read_b32 v184, v246 offset:928
	ds_read_b32 v185, v247 offset:928
	ds_read_b32 v186, v248 offset:928
	ds_read_b32 v187, v249 offset:928
	ds_read_b32 v238, v250 offset:928
	ds_read_b32 v239, v251 offset:928
	ds_read_b32 v240, v252 offset:928
	ds_read_b32 v241, v253 offset:928
	s_waitcnt vmcnt(16)
	v_mfma_f32_16x16x32_bf16 v[76:79], v[76:79], v[6:9], 0
	s_waitcnt vmcnt(12)
	v_mfma_f32_16x16x32_bf16 v[108:111], v[108:111], v[6:9], 0
	v_mfma_f32_16x16x32_bf16 v[76:79], v[10:13], v[2:5], v[76:79]
	v_mfma_f32_16x16x32_bf16 v[10:13], v[104:107], v[2:5], v[108:111]
	s_waitcnt lgkmcnt(0)
	s_and_saveexec_b64 s[6:7], s[12:13]
	s_cbranch_execz .LBB0_1067
	v_lshl_add_u32 v66, v156, 2, v151
	v_mov_b32_e32 v66, v184
	s_nop 0
	s_nop 1
	v_add_f32_e32 v66, v76, v66
.LBB0_1067:
	s_or_b64 exec, exec, s[6:7]
	s_nop 3
	v_or_b32_e32 v76, 1, v94
	v_cmp_ge_u32_e32 vcc, v76, v92
	v_cmp_lt_u32_e64 s[6:7], v76, v93
	v_sub_u32_e32 v76, v76, v67
	s_and_b64 s[14:15], vcc, s[6:7]
	v_med3_i32 v158, v76, -15, 15
	s_and_saveexec_b64 s[6:7], s[14:15]
	s_cbranch_execz .LBB0_1069
	v_lshl_add_u32 v0, v158, 2, v151
	v_mov_b32_e32 v0, v185
	s_nop 0
	v_add_f32_e32 v0, v77, v0
.LBB0_1069:
	s_or_b64 exec, exec, s[6:7]
	v_or_b32_e32 v77, 2, v94
	v_cmp_ge_u32_e32 vcc, v77, v92
	v_cmp_lt_u32_e64 s[6:7], v77, v93
	v_sub_u32_e32 v77, v77, v67
	s_and_b64 s[16:17], vcc, s[6:7]
	v_mov_b32_e32 v76, 0xff800000
	v_med3_i32 v181, v77, -15, 15
	v_mov_b32_e32 v77, 0xff800000
	s_and_saveexec_b64 s[6:7], s[16:17]
	s_cbranch_execz .LBB0_1071
	v_lshl_add_u32 v77, v181, 2, v151
	v_mov_b32_e32 v77, v186
	s_nop 0
	v_add_f32_e32 v77, v78, v77
.LBB0_1071:
	s_or_b64 exec, exec, s[6:7]
	v_or_b32_e32 v78, 3, v94
	v_cmp_ge_u32_e32 vcc, v78, v92
	v_cmp_lt_u32_e64 s[6:7], v78, v93
	v_sub_u32_e32 v78, v78, v67
	s_and_b64 s[18:19], vcc, s[6:7]
	v_med3_i32 v182, v78, -15, 15
	s_and_saveexec_b64 s[6:7], s[18:19]
	s_cbranch_execz .LBB0_1073
	v_lshl_add_u32 v76, v182, 2, v151
	v_mov_b32_e32 v76, v187
	s_nop 0
	v_add_f32_e32 v76, v79, v76
.LBB0_1073:
	s_or_b64 exec, exec, s[6:7]
	v_or_b32_e32 v79, 4, v94
	v_cmp_ge_u32_e32 vcc, v79, v92
	v_cmp_lt_u32_e64 s[6:7], v79, v93
	v_sub_u32_e32 v79, v79, v67
	s_and_b64 s[20:21], vcc, s[6:7]
	v_mov_b32_e32 v78, 0xff800000
	v_med3_i32 v188, v79, -15, 15
	v_mov_b32_e32 v79, 0xff800000
	s_and_saveexec_b64 s[6:7], s[20:21]
	s_cbranch_execz .LBB0_1075
	v_lshl_add_u32 v79, v188, 2, v151
	v_mov_b32_e32 v79, v238
	s_nop 0
	v_add_f32_e32 v79, v10, v79
.LBB0_1075:
	s_or_b64 exec, exec, s[6:7]
	v_or_b32_e32 v10, 5, v94
	v_cmp_ge_u32_e32 vcc, v10, v92
	v_cmp_lt_u32_e64 s[6:7], v10, v93
	v_sub_u32_e32 v10, v10, v67
	s_and_b64 s[22:23], vcc, s[6:7]
	v_med3_i32 v189, v10, -15, 15
	s_and_saveexec_b64 s[6:7], s[22:23]
	s_cbranch_execz .LBB0_1077
	v_lshl_add_u32 v10, v189, 2, v151
	v_mov_b32_e32 v10, v239
	s_nop 0
	v_add_f32_e32 v78, v11, v10
.LBB0_1077:
	s_or_b64 exec, exec, s[6:7]
	v_or_b32_e32 v11, 6, v94
	v_cmp_ge_u32_e32 vcc, v11, v92
	v_cmp_lt_u32_e64 s[6:7], v11, v93
	v_sub_u32_e32 v11, v11, v67
	s_and_b64 s[24:25], vcc, s[6:7]
	v_mov_b32_e32 v10, 0xff800000
	v_med3_i32 v190, v11, -15, 15
	v_mov_b32_e32 v11, 0xff800000
	s_and_saveexec_b64 s[6:7], s[24:25]
	s_cbranch_execz .LBB0_1079
	v_lshl_add_u32 v11, v190, 2, v151
	v_mov_b32_e32 v11, v240
	s_nop 0
	v_add_f32_e32 v11, v12, v11
.LBB0_1079:
	s_or_b64 exec, exec, s[6:7]
	v_or_b32_e32 v12, 7, v94
	v_cmp_ge_u32_e32 vcc, v12, v92
	v_cmp_lt_u32_e64 s[6:7], v12, v93
	v_sub_u32_e32 v120, v12, v67
	s_and_b64 s[6:7], vcc, s[6:7]
	v_med3_i32 v191, v120, -15, 15
	s_and_saveexec_b64 s[34:35], s[6:7]
	s_cbranch_execz .LBB0_1081
	v_med3_i32 v10, v120, -15, 15
	v_lshl_add_u32 v10, v10, 2, v151
	v_mov_b32_e32 v10, v241
	s_nop 0
	v_add_f32_e32 v10, v13, v10
.LBB0_1081:
	s_or_b64 exec, exec, s[34:35]
	ds_read_b32 v184, v246 offset:1052
	ds_read_b32 v185, v247 offset:1052
	ds_read_b32 v186, v248 offset:1052
	ds_read_b32 v187, v249 offset:1052
	ds_read_b32 v238, v250 offset:1052
	ds_read_b32 v239, v251 offset:1052
	ds_read_b32 v240, v252 offset:1052
	ds_read_b32 v241, v253 offset:1052
	v_cmp_lt_i32_e32 vcc, v231, v226
	v_max_f32_e32 v13, v66, v66
	v_max_f32_e32 v67, v77, v77
	v_cndmask_b32_e32 v12, v225, v231, vcc
	v_lshlrev_b32_e32 v137, 2, v12
	v_max_f32_e32 v12, v0, v0
	v_max_f32_e32 v12, v13, v12
	v_max_f32_e32 v13, v76, v76
	v_max_f32_e32 v13, v67, v13
	v_max_f32_e32 v67, v10, v10
	v_max_f32_e32 v92, v11, v11
	v_max_f32_e32 v67, v92, v67
	v_max3_f32 v67, v79, v78, v67
	v_max3_f32 v12, v12, v13, v67
	v_mov_b32_e32 v13, v12
	s_nop 1
	v_permlane16_swap_b32_e32 v13, v12
	v_cmp_lt_i32_e32 vcc, v232, v226
	s_mov_b32 s1, 0xf149f2ca
	v_mov_b32_e32 v149, v1
	v_cndmask_b32_e32 v67, v225, v232, vcc
	s_waitcnt lgkmcnt(0)
	v_max_f32_e32 v13, v13, v13
	v_lshlrev_b32_e32 v139, 2, v67
	v_max_f32_e32 v12, v12, v13
	v_mov_b32_e32 v13, v12
	s_nop 1
	v_permlane32_swap_b32_e32 v13, v12
	v_mov_b32_e32 v145, v1
	v_mfma_f32_16x16x32_bf16 v[34:37], v[34:37], v[6:9], 0
	v_mov_b32_e32 v143, v1
	v_mov_b32_e32 v147, v1
	s_waitcnt lgkmcnt(0)
	v_max3_f32 v121, v12, v13, s1
	v_sub_f32_e32 v0, v0, v121
	v_mul_f32_e32 v0, 0x3fb8aa3b, v0
	v_exp_f32_e32 v155, v0
	v_sub_f32_e32 v0, v77, v121
	v_mul_f32_e32 v0, 0x3fb8aa3b, v0
	v_exp_f32_e32 v157, v0
	v_sub_f32_e32 v0, v76, v121
	v_mul_f32_e32 v0, 0x3fb8aa3b, v0
	v_exp_f32_e32 v159, v0
	v_sub_f32_e32 v0, v79, v121
	v_mul_f32_e32 v0, 0x3fb8aa3b, v0
	v_exp_f32_e32 v160, v0
	v_sub_f32_e32 v0, v78, v121
	v_mul_f32_e32 v0, 0x3fb8aa3b, v0
	v_sub_f32_e32 v12, 0xf149f2ca, v121
	v_sub_f32_e32 v13, v66, v121
	v_exp_f32_e32 v161, v0
	v_sub_f32_e32 v0, v11, v121
	v_mul_f32_e32 v12, 0x3fb8aa3b, v12
	v_mul_f32_e32 v13, 0x3fb8aa3b, v13
	v_mul_f32_e32 v0, 0x3fb8aa3b, v0
	v_exp_f32_e32 v153, v13
	v_exp_f32_e32 v162, v0
	v_exp_f32_e32 v0, v12
	v_sub_f32_e32 v10, v10, v121
	v_mul_f32_e32 v10, 0x3fb8aa3b, v10
	v_exp_f32_e32 v163, v10
	v_mul_f32_e32 v10, 0, v0
	v_add_u32_e32 v0, 0x8000, v155
	v_add_u32_e32 v11, 0x8000, v153
	v_perm_b32 v76, v0, v11, s87
	v_add_u32_e32 v0, 0x8000, v159
	v_add_u32_e32 v11, 0x8000, v157
	v_perm_b32 v77, v0, v11, s87
	v_add_u32_e32 v0, 0x8000, v161
	v_add_u32_e32 v11, 0x8000, v160
	v_perm_b32 v78, v0, v11, s87
	v_add_u32_e32 v0, 0x8000, v163
	v_add_u32_e32 v11, 0x8000, v162
	v_perm_b32 v79, v0, v11, s87
	v_mov_b32_e32 v11, v10
	v_mov_b32_e32 v12, v10
	v_mov_b32_e32 v13, v10
	v_mfma_f32_16x16x32_bf16 v[122:125], v[100:103], v[6:9], 0
	s_nop 0
	v_mfma_f32_16x16x32_bf16 v[116:119], v[50:53], v[76:79], v[10:13]
	v_add_u32_e32 v50, 0xc0, v150
	v_lshlrev_b32_e32 v0, 7, v50
	v_mfma_f32_16x16x32_bf16 v[104:107], v[62:65], v[76:79], v[10:13]
	v_mfma_f32_16x16x32_bf16 v[108:111], v[72:75], v[76:79], v[10:13]
	v_mfma_f32_16x16x32_bf16 v[112:115], v[42:45], v[76:79], v[10:13]
	s_nop 2
	v_lshl_add_u64 v[12:13], s[30:31], 0, v[0:1]
	v_mul_lo_u32 v0, v50, s33
	v_lshl_add_u64 v[42:43], s[28:29], 0, v[0:1]
	v_lshl_add_u64 v[42:43], v[42:43], 0, v[148:149]
	v_lshl_add_u64 v[42:43], v[42:43], 0, v[144:145]
	global_load_dwordx4 v[92:95], v[42:43], off
	global_load_dwordx4 v[72:75], v[42:43], off offset:16
	global_load_dwordx4 v[76:79], v[42:43], off offset:3072
	global_load_dwordx4 v[64:67], v[42:43], off offset:3088
	v_lshl_add_u64 v[12:13], v[12:13], 0, v[142:143]
	v_lshl_add_u64 v[12:13], v[12:13], 0, v[146:147]
	global_load_dwordx4 v[50:53], v[12:13], off
	global_load_dwordx4 v[42:45], v[12:13], off offset:256
	v_mfma_f32_16x16x32_bf16 v[100:103], v[30:33], v[2:5], v[34:37]
	s_nop 2
	global_load_dwordx4 v[34:37], v[12:13], off offset:512
	global_load_dwordx4 v[30:33], v[12:13], off offset:768
	v_mov_b32_e32 v0, 0xff800000
	v_mov_b32_e32 v11, 0xff800000
	v_mfma_f32_16x16x32_bf16 v[96:99], v[96:99], v[2:5], v[122:125]
	s_waitcnt lgkmcnt(0)
	s_and_saveexec_b64 s[34:35], s[12:13]
	s_cbranch_execz .LBB0_1083
	v_lshl_add_u32 v11, v156, 2, v151
	v_mov_b32_e32 v11, v184
	s_nop 0
	v_add_f32_e32 v11, v100, v11
.LBB0_1083:
	s_or_b64 exec, exec, s[34:35]
	s_and_saveexec_b64 s[34:35], s[14:15]
	s_cbranch_execz .LBB0_1085
	v_lshl_add_u32 v0, v158, 2, v151
	v_mov_b32_e32 v0, v185
	s_nop 0
	v_add_f32_e32 v0, v101, v0
.LBB0_1085:
	s_or_b64 exec, exec, s[34:35]
	v_mov_b32_e32 v13, 0xff800000
	v_mov_b32_e32 v62, 0xff800000
	s_and_saveexec_b64 s[34:35], s[16:17]
	s_cbranch_execz .LBB0_1087
	v_lshl_add_u32 v12, v181, 2, v151
	v_mov_b32_e32 v12, v186
	s_nop 0
	v_add_f32_e32 v62, v102, v12
.LBB0_1087:
	s_or_b64 exec, exec, s[34:35]
	s_and_saveexec_b64 s[34:35], s[18:19]
	s_cbranch_execz .LBB0_1089
	v_lshl_add_u32 v12, v182, 2, v151
	v_mov_b32_e32 v12, v187
	s_nop 0
	v_add_f32_e32 v13, v103, v12
.LBB0_1089:
	s_or_b64 exec, exec, s[34:35]
	v_mov_b32_e32 v63, 0xff800000
	v_mov_b32_e32 v100, 0xff800000
	s_and_saveexec_b64 s[34:35], s[20:21]
	s_cbranch_execz .LBB0_1091
	v_lshl_add_u32 v12, v188, 2, v151
	v_mov_b32_e32 v12, v238
	s_nop 0
	v_add_f32_e32 v100, v96, v12
.LBB0_1091:
	s_or_b64 exec, exec, s[34:35]
	s_and_saveexec_b64 s[34:35], s[22:23]
	s_cbranch_execz .LBB0_1093
	v_lshl_add_u32 v12, v189, 2, v151
	v_mov_b32_e32 v12, v239
	s_nop 0
	v_add_f32_e32 v63, v97, v12
.LBB0_1093:
	s_or_b64 exec, exec, s[34:35]
	v_mov_b32_e32 v96, 0xff800000
	v_mov_b32_e32 v97, 0xff800000
	s_and_saveexec_b64 s[34:35], s[24:25]
	s_cbranch_execz .LBB0_1095
	v_lshl_add_u32 v12, v190, 2, v151
	v_mov_b32_e32 v12, v240
	s_nop 0
	v_add_f32_e32 v97, v98, v12
.LBB0_1095:
	s_or_b64 exec, exec, s[34:35]
	s_and_saveexec_b64 s[34:35], s[6:7]
	s_cbranch_execz .LBB0_1097
	v_med3_i32 v12, v120, -15, 15
	v_lshl_add_u32 v12, v12, 2, v151
	v_mov_b32_e32 v12, v241
	s_nop 0
	v_add_f32_e32 v96, v99, v12
.LBB0_1097:
	s_or_b64 exec, exec, s[34:35]
	ds_read_b32 v184, v246 offset:1176
	ds_read_b32 v185, v247 offset:1176
	ds_read_b32 v186, v248 offset:1176
	ds_read_b32 v187, v249 offset:1176
	ds_read_b32 v238, v250 offset:1176
	ds_read_b32 v239, v251 offset:1176
	ds_read_b32 v240, v252 offset:1176
	ds_read_b32 v241, v253 offset:1176
	v_max_f32_e32 v12, v0, v0
	v_max_f32_e32 v98, v11, v11
	v_max_f32_e32 v12, v98, v12
	v_max_f32_e32 v98, v13, v13
	v_max_f32_e32 v99, v62, v62
	v_max_f32_e32 v98, v99, v98
	v_max_f32_e32 v99, v96, v96
	v_max_f32_e32 v101, v97, v97
	v_max_f32_e32 v99, v101, v99
	v_max3_f32 v99, v100, v63, v99
	v_max3_f32 v12, v12, v98, v99
	v_mov_b32_e32 v98, v12
	s_nop 1
	v_permlane16_swap_b32_e32 v98, v12
	v_mov_b32_e32 v149, v1
	v_mov_b32_e32 v145, v1
	v_mov_b32_e32 v143, v1
	v_mov_b32_e32 v147, v1
	s_waitcnt lgkmcnt(0)
	v_max_f32_e32 v98, v98, v98
	v_max_f32_e32 v12, v12, v98
	v_mov_b32_e32 v98, v12
	s_nop 1
	v_permlane32_swap_b32_e32 v98, v12
	s_waitcnt vmcnt(14)
	v_mfma_f32_16x16x32_bf16 v[122:125], v[46:49], v[6:9], 0
	s_waitcnt lgkmcnt(0)
	v_max3_f32 v12, v121, v12, v98
	v_sub_f32_e32 v0, v0, v12
	v_mul_f32_e32 v0, 0x3fb8aa3b, v0
	v_exp_f32_e32 v164, v0
	v_sub_f32_e32 v0, v62, v12
	v_mul_f32_e32 v0, 0x3fb8aa3b, v0
	v_exp_f32_e32 v165, v0
	v_sub_f32_e32 v0, v13, v12
	v_mul_f32_e32 v0, 0x3fb8aa3b, v0
	v_exp_f32_e32 v166, v0
	v_sub_f32_e32 v0, v100, v12
	v_mul_f32_e32 v0, 0x3fb8aa3b, v0
	v_exp_f32_e32 v167, v0
	v_sub_f32_e32 v0, v63, v12
	v_sub_f32_e32 v11, v11, v12
	v_mul_f32_e32 v0, 0x3fb8aa3b, v0
	v_mul_f32_e32 v11, 0x3fb8aa3b, v11
	v_exp_f32_e32 v168, v0
	v_sub_f32_e32 v0, v97, v12
	v_exp_f32_e32 v11, v11
	v_mul_f32_e32 v0, 0x3fb8aa3b, v0
	v_exp_f32_e32 v169, v0
	v_sub_f32_e32 v0, v96, v12
	v_sub_f32_e32 v98, v121, v12
	v_mul_f32_e32 v0, 0x3fb8aa3b, v0
	v_mul_f32_e32 v98, 0x3fb8aa3b, v98
	v_exp_f32_e32 v170, v0
	v_exp_f32_e32 v152, v98
	v_add_u32_e32 v0, 0x8000, v164
	v_add_u32_e32 v13, 0x8000, v11
	v_perm_b32 v96, v0, v13, s87
	v_add_u32_e32 v0, 0x8000, v166
	v_add_u32_e32 v13, 0x8000, v165
	v_perm_b32 v97, v0, v13, s87
	v_add_u32_e32 v0, 0x8000, v168
	v_add_u32_e32 v13, 0x8000, v167
	v_perm_b32 v98, v0, v13, s87
	v_add_u32_e32 v0, 0x8000, v170
	v_add_u32_e32 v13, 0x8000, v169
	v_perm_b32 v99, v0, v13, s87
	v_pk_mul_f32 v[102:103], v[118:119], v[152:153] op_sel_hi:[1,0]
	v_pk_mul_f32 v[100:101], v[116:117], v[152:153] op_sel_hi:[1,0]
	v_add_u32_e32 v13, 0x100, v150
	v_lshlrev_b32_e32 v0, 7, v13
	v_mfma_f32_16x16x32_bf16 v[100:103], v[88:91], v[96:99], v[100:103]
	v_mul_f32_e64 v90, v106, v152
	v_mul_f32_e64 v91, v107, v152
	v_pk_mul_f32 v[88:89], v[104:105], v[152:153] op_sel_hi:[1,0]
	v_lshl_add_u64 v[62:63], s[30:31], 0, v[0:1]
	v_mul_lo_u32 v0, v13, s33
	v_mfma_f32_16x16x32_bf16 v[104:107], v[84:87], v[96:99], v[88:91]
	v_mul_f32_e64 v86, v110, v152
	v_mul_f32_e64 v87, v111, v152
	v_pk_mul_f32 v[84:85], v[108:109], v[152:153] op_sel_hi:[1,0]
	v_mov_b32_e32 v13, 0xff800000
	s_waitcnt vmcnt(13)
	v_mfma_f32_16x16x32_bf16 v[116:119], v[58:61], v[6:9], 0
	v_lshl_add_u64 v[58:59], v[62:63], 0, v[142:143]
	v_lshl_add_u64 v[58:59], v[58:59], 0, v[146:147]
	v_mfma_f32_16x16x32_bf16 v[108:111], v[80:83], v[96:99], v[84:87]
	v_mul_f32_e64 v82, v114, v152
	v_mul_f32_e64 v83, v115, v152
	v_pk_mul_f32 v[80:81], v[112:113], v[152:153] op_sel_hi:[1,0]
	v_mfma_f32_16x16x32_bf16 v[116:119], v[38:41], v[2:5], v[116:119]
	s_nop 0
	v_mfma_f32_16x16x32_bf16 v[112:115], v[68:71], v[96:99], v[80:83]
	v_lshl_add_u64 v[68:69], s[28:29], 0, v[0:1]
	v_lshl_add_u64 v[68:69], v[68:69], 0, v[148:149]
	v_lshl_add_u64 v[68:69], v[68:69], 0, v[144:145]
	global_load_dwordx4 v[96:99], v[68:69], off
	global_load_dwordx4 v[84:87], v[68:69], off offset:16
	global_load_dwordx4 v[88:91], v[68:69], off offset:3072
	global_load_dwordx4 v[80:83], v[68:69], off offset:3088
	s_nop 0
	global_load_dwordx4 v[68:71], v[58:59], off
	global_load_dwordx4 v[60:63], v[58:59], off offset:256
	global_load_dwordx4 v[46:49], v[58:59], off offset:512
	global_load_dwordx4 v[38:41], v[58:59], off offset:768
	s_waitcnt vmcnt(20)
	v_mfma_f32_16x16x32_bf16 v[54:57], v[54:57], v[2:5], v[122:125]
	v_mov_b32_e32 v0, 0xff800000
	s_waitcnt lgkmcnt(0)
	s_and_saveexec_b64 s[34:35], s[12:13]
	s_cbranch_execz .LBB0_1099
	v_lshl_add_u32 v13, v156, 2, v151
	v_mov_b32_e32 v13, v184
	s_nop 0
	v_add_f32_e32 v13, v116, v13
.LBB0_1099:
	s_or_b64 exec, exec, s[34:35]
	s_and_saveexec_b64 s[34:35], s[14:15]
	s_cbranch_execz .LBB0_1101
	v_lshl_add_u32 v0, v158, 2, v151
	v_mov_b32_e32 v0, v185
	s_nop 0
	v_add_f32_e32 v0, v117, v0
.LBB0_1101:
	s_or_b64 exec, exec, s[34:35]
	v_mov_b32_e32 v58, 0xff800000
	v_mov_b32_e32 v59, 0xff800000
	s_and_saveexec_b64 s[34:35], s[16:17]
	s_cbranch_execz .LBB0_1103
	v_lshl_add_u32 v59, v181, 2, v151
	v_mov_b32_e32 v59, v186
	s_nop 0
	v_add_f32_e32 v59, v118, v59
.LBB0_1103:
	s_or_b64 exec, exec, s[34:35]
	s_and_saveexec_b64 s[34:35], s[18:19]
	s_cbranch_execz .LBB0_1105
	v_lshl_add_u32 v58, v182, 2, v151
	v_mov_b32_e32 v58, v187
	s_nop 0
	v_add_f32_e32 v58, v119, v58
.LBB0_1105:
	s_or_b64 exec, exec, s[34:35]
	v_mov_b32_e32 v116, 0xff800000
	v_mov_b32_e32 v117, 0xff800000
	s_and_saveexec_b64 s[34:35], s[20:21]
	s_cbranch_execz .LBB0_1190
	v_lshl_add_u32 v117, v188, 2, v151
	v_mov_b32_e32 v117, v238
	s_nop 0
	v_add_f32_e32 v117, v54, v117
	s_or_b64 exec, exec, s[34:35]
	s_and_saveexec_b64 s[34:35], s[22:23]
	s_cbranch_execnz .LBB0_1191

.LBB0_1108:
	v_lshl_add_u32 v54, v190, 2, v151
	v_mov_b32_e32 v54, v240
	s_nop 0
	v_add_f32_e32 v118, v56, v54
.LBB0_1109:
	s_or_b64 exec, exec, s[34:35]
	s_xor_b64 s[2:3], s[6:7], -1
	s_and_saveexec_b64 s[34:35], s[2:3]
	s_xor_b64 s[34:35], exec, s[34:35]
	v_med3_i32 v191, v120, -15, 15
	s_or_saveexec_b64 s[34:35], s[34:35]
	v_mov_b32_e32 v54, 0xff800000
	v_mov_b32_e32 v55, 0xff800000
	s_xor_b64 exec, exec, s[34:35]
	s_cbranch_execz .LBB0_1113
	v_lshl_add_u32 v55, v191, 2, v151
	v_mov_b32_e32 v55, v241
	s_nop 0
	v_add_f32_e32 v55, v57, v55
.LBB0_1113:
	s_or_b64 exec, exec, s[34:35]
	ds_read_b32 v184, v246 offset:1300
	ds_read_b32 v185, v247 offset:1300
	ds_read_b32 v186, v248 offset:1300
	ds_read_b32 v187, v249 offset:1300
	ds_read_b32 v238, v250 offset:1300
	ds_read_b32 v239, v251 offset:1300
	ds_read_b32 v240, v252 offset:1300
	ds_read_b32 v241, v253 offset:1300
	v_max_f32_e32 v56, v0, v0
	v_max_f32_e32 v57, v13, v13
	v_max_f32_e32 v56, v57, v56
	v_max_f32_e32 v57, v58, v58
	v_max_f32_e32 v119, v59, v59
	v_max_f32_e32 v57, v119, v57
	v_max_f32_e32 v119, v55, v55
	v_max_f32_e32 v120, v118, v118
	v_max_f32_e32 v119, v120, v119
	v_max3_f32 v119, v117, v116, v119
	v_max3_f32 v56, v56, v57, v119
	v_mov_b32_e32 v57, v56
	s_nop 1
	v_permlane16_swap_b32_e32 v57, v56
	v_mov_b32_e32 v149, v1
	v_mov_b32_e32 v145, v1
	v_mov_b32_e32 v143, v1
	v_mov_b32_e32 v147, v1
	s_waitcnt lgkmcnt(0)
	v_max_f32_e32 v57, v57, v57
	v_max_f32_e32 v56, v56, v57
	v_mov_b32_e32 v57, v56
	s_nop 1
	v_permlane32_swap_b32_e32 v57, v56
	s_waitcnt vmcnt(13)
	v_mfma_f32_16x16x32_bf16 v[76:79], v[76:79], v[6:9], 0
	v_lshl_add_u32 v179, v156, 2, v151
	s_waitcnt lgkmcnt(0)
	v_max3_f32 v193, v12, v56, v57
	v_sub_f32_e32 v0, v0, v193
	v_mul_f32_e32 v0, 0x3fb8aa3b, v0
	v_exp_f32_e32 v172, v0
	v_sub_f32_e32 v0, v59, v193
	v_mul_f32_e32 v0, 0x3fb8aa3b, v0
	v_exp_f32_e32 v173, v0
	v_sub_f32_e32 v0, v58, v193
	v_mul_f32_e32 v0, 0x3fb8aa3b, v0
	v_exp_f32_e32 v174, v0
	v_sub_f32_e32 v0, v117, v193
	v_mul_f32_e32 v0, 0x3fb8aa3b, v0
	v_exp_f32_e32 v175, v0
	v_sub_f32_e32 v0, v116, v193
	v_sub_f32_e32 v13, v13, v193
	v_mul_f32_e32 v0, 0x3fb8aa3b, v0
	v_mul_f32_e32 v13, 0x3fb8aa3b, v13
	v_exp_f32_e32 v176, v0
	v_sub_f32_e32 v0, v118, v193
	v_exp_f32_e32 v171, v13
	v_mul_f32_e32 v0, 0x3fb8aa3b, v0
	v_exp_f32_e32 v177, v0
	v_sub_f32_e32 v0, v55, v193
	v_sub_f32_e32 v12, v12, v193
	v_mul_f32_e32 v0, 0x3fb8aa3b, v0
	v_mul_f32_e32 v12, 0x3fb8aa3b, v12
	v_exp_f32_e32 v178, v0
	v_exp_f32_e32 v154, v12
	v_add_u32_e32 v0, 0x8000, v172
	v_add_u32_e32 v12, 0x8000, v171
	v_perm_b32 v56, v0, v12, s87
	v_add_u32_e32 v0, 0x8000, v174
	v_add_u32_e32 v12, 0x8000, v173
	v_perm_b32 v57, v0, v12, s87
	v_add_u32_e32 v0, 0x8000, v176
	v_add_u32_e32 v12, 0x8000, v175
	v_perm_b32 v58, v0, v12, s87
	v_add_u32_e32 v0, 0x8000, v178
	v_add_u32_e32 v12, 0x8000, v177
	v_perm_b32 v59, v0, v12, s87
	v_pk_mul_f32 v[102:103], v[102:103], v[154:155] op_sel_hi:[1,0]
	v_pk_mul_f32 v[100:101], v[100:101], v[154:155] op_sel_hi:[1,0]
	v_add_u32_e32 v12, 0x140, v150
	v_lshlrev_b32_e32 v0, 7, v12
	v_mfma_f32_16x16x32_bf16 v[26:29], v[26:29], v[56:59], v[100:103]
	s_nop 2
	v_mul_f32_e64 v102, v106, v154
	v_mul_f32_e64 v103, v107, v154
	v_pk_mul_f32 v[100:101], v[104:105], v[154:155] op_sel_hi:[1,0]
	s_waitcnt vmcnt(12)
	v_mfma_f32_16x16x32_bf16 v[64:67], v[64:67], v[2:5], v[76:79]
	v_mfma_f32_16x16x32_bf16 v[100:103], v[22:25], v[56:59], v[100:103]
	v_mul_f32_e64 v24, v110, v154
	v_mul_f32_e64 v25, v111, v154
	v_pk_mul_f32 v[22:23], v[108:109], v[154:155] op_sel_hi:[1,0]
	s_nop 1
	v_mfma_f32_16x16x32_bf16 v[104:107], v[18:21], v[56:59], v[22:25]
	v_mul_f32_e64 v20, v114, v154
	v_mul_f32_e64 v21, v115, v154
	v_pk_mul_f32 v[18:19], v[112:113], v[154:155] op_sel_hi:[1,0]
	s_nop 1
	v_mfma_f32_16x16x32_bf16 v[108:111], v[14:17], v[56:59], v[18:21]
	v_lshl_add_u64 v[16:17], s[30:31], 0, v[0:1]
	v_mul_lo_u32 v0, v12, s33
	v_lshl_add_u64 v[12:13], s[28:29], 0, v[0:1]
	v_lshl_add_u64 v[12:13], v[12:13], 0, v[148:149]
	v_lshl_add_u64 v[12:13], v[12:13], 0, v[144:145]
	global_load_dwordx4 v[128:131], v[12:13], off
	global_load_dwordx4 v[120:123], v[12:13], off offset:16
	global_load_dwordx4 v[124:127], v[12:13], off offset:3072
	global_load_dwordx4 v[116:119], v[12:13], off offset:3088
	v_mfma_f32_16x16x32_bf16 v[12:15], v[92:95], v[6:9], 0
	v_lshl_add_u64 v[16:17], v[16:17], 0, v[142:143]
	v_lshl_add_u64 v[24:25], v[16:17], 0, v[146:147]
	global_load_dwordx4 v[56:59], v[24:25], off
	global_load_dwordx4 v[20:23], v[24:25], off offset:256
	v_mfma_f32_16x16x32_bf16 v[72:75], v[72:75], v[2:5], v[12:15]
	global_load_dwordx4 v[16:19], v[24:25], off offset:512
	s_nop 1
	global_load_dwordx4 v[12:15], v[24:25], off offset:768
	s_waitcnt lgkmcnt(0)
	s_and_saveexec_b64 s[34:35], s[12:13]
	s_cbranch_execz .LBB0_1115
	v_mov_b32_e32 v0, v184
	s_nop 0
	v_add_f32_e32 v54, v72, v0
.LBB0_1115:
	s_or_b64 exec, exec, s[34:35]
	v_mov_b32_e32 v0, 0xff800000
	v_lshl_add_u32 v180, v158, 2, v151
	v_mov_b32_e32 v24, 0xff800000
	s_and_saveexec_b64 s[34:35], s[14:15]
	s_cbranch_execz .LBB0_1117
	v_mov_b32_e32 v24, v185
	s_nop 0
	v_add_f32_e32 v24, v73, v24
.LBB0_1117:
	s_or_b64 exec, exec, s[34:35]
	v_lshl_add_u32 v181, v181, 2, v151
	s_and_saveexec_b64 s[34:35], s[16:17]
	s_cbranch_execz .LBB0_1119
	v_mov_b32_e32 v0, v186
	s_nop 0
	v_add_f32_e32 v0, v74, v0
.LBB0_1119:
	s_or_b64 exec, exec, s[34:35]
	v_mov_b32_e32 v25, 0xff800000
	v_lshl_add_u32 v182, v182, 2, v151
	v_mov_b32_e32 v72, 0xff800000
	s_and_saveexec_b64 s[34:35], s[18:19]
	s_cbranch_execz .LBB0_1121
	v_mov_b32_e32 v55, v187
	s_nop 0
	v_add_f32_e32 v72, v75, v55
.LBB0_1121:
	s_or_b64 exec, exec, s[34:35]
	v_lshl_add_u32 v188, v188, 2, v151
	s_and_saveexec_b64 s[34:35], s[20:21]
	s_cbranch_execz .LBB0_1123
	v_mov_b32_e32 v25, v238
	s_nop 0
	v_add_f32_e32 v25, v64, v25
.LBB0_1123:
	s_or_b64 exec, exec, s[34:35]
	v_mov_b32_e32 v64, 0xff800000
	v_lshl_add_u32 v189, v189, 2, v151
	v_mov_b32_e32 v73, 0xff800000
	s_and_saveexec_b64 s[34:35], s[22:23]
	s_cbranch_execz .LBB0_1125
	v_mov_b32_e32 v55, v239
	s_nop 0
	v_add_f32_e32 v73, v65, v55
.LBB0_1125:
	s_or_b64 exec, exec, s[34:35]
	v_lshl_add_u32 v190, v190, 2, v151
	s_and_saveexec_b64 s[34:35], s[24:25]
	s_cbranch_execz .LBB0_1127
	v_mov_b32_e32 v55, v240
	s_nop 0
	v_add_f32_e32 v64, v66, v55
.LBB0_1127:
	s_or_b64 exec, exec, s[34:35]
	v_mov_b32_e32 v55, 0xff800000
	v_lshl_add_u32 v192, v191, 2, v151
	v_mov_b32_e32 v65, 0xff800000
	s_and_saveexec_b64 s[34:35], s[6:7]
	s_cbranch_execz .LBB0_1129
	v_mov_b32_e32 v65, v241
	s_nop 0
	v_add_f32_e32 v65, v67, v65
.LBB0_1129:
	s_or_b64 exec, exec, s[34:35]
	ds_read_b32 v184, v246 offset:1424
	ds_read_b32 v185, v247 offset:1424
	ds_read_b32 v186, v248 offset:1424
	ds_read_b32 v187, v249 offset:1424
	ds_read_b32 v238, v250 offset:1424
	ds_read_b32 v239, v251 offset:1424
	ds_read_b32 v240, v252 offset:1424
	ds_read_b32 v241, v253 offset:1424
	v_max_f32_e32 v66, v24, v24
	v_max_f32_e32 v67, v54, v54
	v_max_f32_e32 v66, v67, v66
	v_max_f32_e32 v67, v72, v72
	v_max_f32_e32 v74, v0, v0
	v_max_f32_e32 v67, v74, v67
	v_max_f32_e32 v74, v65, v65
	v_max_f32_e32 v75, v64, v64
	v_max_f32_e32 v74, v75, v74
	v_max3_f32 v74, v25, v73, v74
	v_max3_f32 v66, v66, v67, v74
	v_mov_b32_e32 v67, v66
	s_nop 1
	v_permlane16_swap_b32_e32 v67, v66
	v_mov_b32_e32 v149, v1
	v_mov_b32_e32 v145, v1
	v_mov_b32_e32 v143, v1
	v_mov_b32_e32 v147, v1
	s_waitcnt lgkmcnt(0)
	v_max_f32_e32 v67, v67, v67
	v_max_f32_e32 v66, v66, v67
	v_mov_b32_e32 v67, v66
	s_nop 1
	v_permlane32_swap_b32_e32 v67, v66
	s_waitcnt vmcnt(13)
	v_mfma_f32_16x16x32_bf16 v[88:91], v[88:91], v[6:9], 0
	s_waitcnt lgkmcnt(0)
	v_max3_f32 v158, v193, v66, v67
	v_sub_f32_e32 v0, v0, v158
	v_mul_f32_e32 v0, 0x3fb8aa3b, v0
	v_exp_f32_e32 v194, v0
	v_sub_f32_e32 v0, v72, v158
	v_mul_f32_e32 v0, 0x3fb8aa3b, v0
	v_exp_f32_e32 v195, v0
	v_sub_f32_e32 v0, v25, v158
	v_mul_f32_e32 v0, 0x3fb8aa3b, v0
	v_exp_f32_e32 v196, v0
	v_sub_f32_e32 v0, v73, v158
	v_sub_f32_e32 v54, v54, v158
	v_sub_f32_e32 v24, v24, v158
	v_mul_f32_e32 v0, 0x3fb8aa3b, v0
	v_mul_f32_e32 v54, 0x3fb8aa3b, v54
	v_mul_f32_e32 v24, 0x3fb8aa3b, v24
	v_exp_f32_e32 v197, v0
	v_sub_f32_e32 v0, v64, v158
	v_sub_f32_e32 v66, v193, v158
	v_exp_f32_e32 v191, v54
	v_exp_f32_e32 v193, v24
	v_mul_f32_e32 v0, 0x3fb8aa3b, v0
	v_exp_f32_e32 v198, v0
	v_sub_f32_e32 v0, v65, v158
	v_mul_f32_e32 v0, 0x3fb8aa3b, v0
	v_mul_f32_e32 v66, 0x3fb8aa3b, v66
	v_exp_f32_e32 v199, v0
	v_exp_f32_e32 v156, v66
	v_add_u32_e32 v0, 0x8000, v193
	v_add_u32_e32 v24, 0x8000, v191
	v_perm_b32 v64, v0, v24, s87
	v_add_u32_e32 v0, 0x8000, v195
	v_add_u32_e32 v24, 0x8000, v194
	v_perm_b32 v65, v0, v24, s87
	v_add_u32_e32 v0, 0x8000, v197
	v_add_u32_e32 v24, 0x8000, v196
	v_perm_b32 v66, v0, v24, s87
	v_add_u32_e32 v0, 0x8000, v199
	v_add_u32_e32 v24, 0x8000, v198
	v_perm_b32 v67, v0, v24, s87
	v_pk_mul_f32 v[28:29], v[28:29], v[156:157] op_sel_hi:[1,0]
	v_pk_mul_f32 v[26:27], v[26:27], v[156:157] op_sel_hi:[1,0]
	v_pk_mul_f32 v[24:25], v[100:101], v[156:157] op_sel_hi:[1,0]
	s_waitcnt vmcnt(12)
	v_mfma_f32_16x16x32_bf16 v[80:83], v[80:83], v[2:5], v[88:91]
	v_mfma_f32_16x16x32_bf16 v[50:53], v[50:53], v[64:67], v[26:29]
	s_nop 2
	v_mul_f32_e64 v26, v102, v156
	v_mul_f32_e64 v27, v103, v156
	s_nop 1
	v_mfma_f32_16x16x32_bf16 v[42:45], v[42:45], v[64:67], v[24:27]
	s_nop 2
	v_mul_f32_e64 v26, v106, v156
	v_mul_f32_e64 v27, v107, v156
	v_pk_mul_f32 v[24:25], v[104:105], v[156:157] op_sel_hi:[1,0]
	s_nop 1
	v_mfma_f32_16x16x32_bf16 v[92:95], v[34:37], v[64:67], v[24:27]
	s_nop 2
	v_mul_f32_e64 v26, v110, v156
	v_mul_f32_e64 v27, v111, v156
	v_pk_mul_f32 v[24:25], v[108:109], v[156:157] op_sel_hi:[1,0]
	s_nop 1
	v_mfma_f32_16x16x32_bf16 v[100:103], v[30:33], v[64:67], v[24:27]
	s_nop 2
	v_add_u32_e32 v24, 0x180, v150
	v_lshlrev_b32_e32 v0, 7, v24
	v_lshl_add_u64 v[36:37], s[30:31], 0, v[0:1]
	v_mul_lo_u32 v0, v24, s33
	v_lshl_add_u64 v[24:25], s[28:29], 0, v[0:1]
	v_lshl_add_u64 v[24:25], v[24:25], 0, v[148:149]
	v_lshl_add_u64 v[24:25], v[24:25], 0, v[144:145]
	global_load_dwordx4 v[112:115], v[24:25], off
	global_load_dwordx4 v[28:31], v[24:25], off offset:16
	global_load_dwordx4 v[32:35], v[24:25], off offset:3072
	global_load_dwordx4 v[104:107], v[24:25], off offset:3088
	v_mfma_f32_16x16x32_bf16 v[24:27], v[96:99], v[6:9], 0
	v_lshl_add_u64 v[36:37], v[36:37], 0, v[142:143]
	v_lshl_add_u64 v[36:37], v[36:37], 0, v[146:147]
	global_load_dwordx4 v[76:79], v[36:37], off
	global_load_dwordx4 v[72:75], v[36:37], off offset:256
	v_mfma_f32_16x16x32_bf16 v[84:87], v[84:87], v[2:5], v[24:27]
	global_load_dwordx4 v[64:67], v[36:37], off offset:512
	s_nop 1
	global_load_dwordx4 v[24:27], v[36:37], off offset:768
	s_waitcnt lgkmcnt(0)
	s_and_saveexec_b64 s[34:35], s[12:13]
	s_cbranch_execz .LBB0_1131
	v_mov_b32_e32 v0, v184
	s_nop 0
	v_add_f32_e32 v55, v84, v0
.LBB0_1131:
	s_or_b64 exec, exec, s[34:35]
	v_mov_b32_e32 v0, 0xff800000
	v_mov_b32_e32 v36, 0xff800000
	s_and_saveexec_b64 s[34:35], s[14:15]
	s_cbranch_execz .LBB0_1133
	v_mov_b32_e32 v36, v185
	s_nop 0
	v_add_f32_e32 v36, v85, v36
.LBB0_1133:
	s_or_b64 exec, exec, s[34:35]
	s_and_saveexec_b64 s[34:35], s[16:17]
	s_cbranch_execz .LBB0_1135
	v_mov_b32_e32 v0, v186
	s_nop 0
	v_add_f32_e32 v0, v86, v0
.LBB0_1135:
	s_or_b64 exec, exec, s[34:35]
	v_mov_b32_e32 v37, 0xff800000
	v_mov_b32_e32 v54, 0xff800000
	s_and_saveexec_b64 s[34:35], s[18:19]
	s_cbranch_execz .LBB0_1137
	v_mov_b32_e32 v54, v187
	s_nop 0
	v_add_f32_e32 v54, v87, v54
.LBB0_1137:
	s_or_b64 exec, exec, s[34:35]
	s_and_saveexec_b64 s[34:35], s[20:21]
	s_cbranch_execz .LBB0_1139
	v_mov_b32_e32 v37, v238
	s_nop 0
	v_add_f32_e32 v37, v80, v37
.LBB0_1139:
	s_or_b64 exec, exec, s[34:35]
	v_mov_b32_e32 v80, 0xff800000
	v_mov_b32_e32 v84, 0xff800000
	s_and_saveexec_b64 s[34:35], s[22:23]
	s_cbranch_execz .LBB0_1141
	v_mov_b32_e32 v84, v239
	s_nop 0
	v_add_f32_e32 v84, v81, v84
.LBB0_1141:
	s_or_b64 exec, exec, s[34:35]
	s_and_saveexec_b64 s[34:35], s[24:25]
	s_cbranch_execz .LBB0_1143
	v_mov_b32_e32 v80, v240
	s_nop 0
	v_add_f32_e32 v80, v82, v80
.LBB0_1143:
	s_or_b64 exec, exec, s[34:35]
	v_mov_b32_e32 v151, 0xff800000
	v_mov_b32_e32 v81, 0xff800000
	s_and_saveexec_b64 s[34:35], s[6:7]
	s_cbranch_execz .LBB0_1145
	v_mov_b32_e32 v81, v241
	s_nop 0
	v_add_f32_e32 v81, v83, v81
.LBB0_1145:
	s_or_b64 exec, exec, s[34:35]
	ds_read_b32 v184, v246 offset:1548
	ds_read_b32 v185, v247 offset:1548
	ds_read_b32 v186, v248 offset:1548
	ds_read_b32 v187, v249 offset:1548
	ds_read_b32 v238, v250 offset:1548
	ds_read_b32 v239, v251 offset:1548
	ds_read_b32 v240, v252 offset:1548
	ds_read_b32 v241, v253 offset:1548
	v_max_f32_e32 v82, v36, v36
	v_max_f32_e32 v83, v55, v55
	v_max_f32_e32 v82, v83, v82
	v_max_f32_e32 v83, v54, v54
	v_max_f32_e32 v85, v0, v0
	v_max_f32_e32 v83, v85, v83
	v_max_f32_e32 v85, v81, v81
	v_max_f32_e32 v86, v80, v80
	v_max_f32_e32 v85, v86, v85
	v_max3_f32 v85, v37, v84, v85
	v_max3_f32 v82, v82, v83, v85
	v_mov_b32_e32 v83, v82
	s_nop 1
	v_permlane16_swap_b32_e32 v83, v82
	v_mov_b32_e32 v149, v1
	v_mov_b32_e32 v145, v1
	v_mov_b32_e32 v143, v1
	v_mov_b32_e32 v147, v1
	s_waitcnt lgkmcnt(0)
	v_max_f32_e32 v83, v83, v83
	v_max_f32_e32 v82, v82, v83
	v_mov_b32_e32 v83, v82
	s_nop 1
	v_permlane32_swap_b32_e32 v83, v82
	s_waitcnt vmcnt(13)
	v_mfma_f32_16x16x32_bf16 v[124:127], v[124:127], v[6:9], 0
	s_waitcnt lgkmcnt(0)
	v_max3_f32 v208, v158, v82, v83
	v_sub_f32_e32 v0, v0, v208
	v_mul_f32_e32 v0, 0x3fb8aa3b, v0
	v_exp_f32_e32 v202, v0
	v_sub_f32_e32 v0, v54, v208
	v_mul_f32_e32 v0, 0x3fb8aa3b, v0
	v_exp_f32_e32 v203, v0
	v_sub_f32_e32 v0, v37, v208
	v_mul_f32_e32 v0, 0x3fb8aa3b, v0
	v_exp_f32_e32 v204, v0
	v_sub_f32_e32 v0, v84, v208
	v_sub_f32_e32 v55, v55, v208
	v_sub_f32_e32 v36, v36, v208
	v_mul_f32_e32 v0, 0x3fb8aa3b, v0
	v_mul_f32_e32 v55, 0x3fb8aa3b, v55
	v_mul_f32_e32 v36, 0x3fb8aa3b, v36
	v_exp_f32_e32 v205, v0
	v_sub_f32_e32 v0, v80, v208
	v_exp_f32_e32 v200, v55
	v_exp_f32_e32 v201, v36
	v_mul_f32_e32 v0, 0x3fb8aa3b, v0
	v_exp_f32_e32 v206, v0
	v_sub_f32_e32 v0, v81, v208
	v_sub_f32_e32 v82, v158, v208
	v_mul_f32_e32 v0, 0x3fb8aa3b, v0
	v_mul_f32_e32 v82, 0x3fb8aa3b, v82
	v_exp_f32_e32 v207, v0
	v_exp_f32_e32 v158, v82
	v_add_u32_e32 v0, 0x8000, v201
	v_add_u32_e32 v36, 0x8000, v200
	v_perm_b32 v88, v0, v36, s87
	v_add_u32_e32 v0, 0x8000, v203
	v_add_u32_e32 v36, 0x8000, v202
	v_perm_b32 v89, v0, v36, s87
	v_add_u32_e32 v0, 0x8000, v205
	v_add_u32_e32 v36, 0x8000, v204
	v_perm_b32 v90, v0, v36, s87
	v_add_u32_e32 v0, 0x8000, v207
	v_add_u32_e32 v36, 0x8000, v206
	v_perm_b32 v91, v0, v36, s87
	v_pk_mul_f32 v[44:45], v[44:45], v[158:159] op_sel_hi:[1,0]
	v_pk_mul_f32 v[42:43], v[42:43], v[158:159] op_sel_hi:[1,0]
	v_pk_mul_f32 v[52:53], v[52:53], v[158:159] op_sel_hi:[1,0]
	v_pk_mul_f32 v[50:51], v[50:51], v[158:159] op_sel_hi:[1,0]
	v_mfma_f32_16x16x32_bf16 v[80:83], v[60:63], v[88:91], v[42:45]
	s_nop 2
	v_mul_f32_e64 v44, v94, v158
	v_mul_f32_e64 v45, v95, v158
	v_pk_mul_f32 v[42:43], v[92:93], v[158:159] op_sel_hi:[1,0]
	v_mfma_f32_16x16x32_bf16 v[84:87], v[68:71], v[88:91], v[50:53]
	s_nop 0
	v_mfma_f32_16x16x32_bf16 v[68:71], v[46:49], v[88:91], v[42:45]
	s_nop 2
	v_mul_f32_e64 v44, v102, v158
	v_mul_f32_e64 v45, v103, v158
	v_pk_mul_f32 v[42:43], v[100:101], v[158:159] op_sel_hi:[1,0]
	s_nop 1
	v_mfma_f32_16x16x32_bf16 v[36:39], v[38:41], v[88:91], v[42:45]
	v_add_u32_e32 v40, 0x1c0, v150
	v_lshlrev_b32_e32 v0, 7, v40
	s_nop 0
	v_lshl_add_u64 v[44:45], s[30:31], 0, v[0:1]
	v_mul_lo_u32 v0, v40, s33
	v_lshl_add_u64 v[40:41], s[28:29], 0, v[0:1]
	v_lshl_add_u64 v[40:41], v[40:41], 0, v[148:149]
	v_lshl_add_u64 v[40:41], v[40:41], 0, v[144:145]
	global_load_dwordx4 v[108:111], v[40:41], off
	global_load_dwordx4 v[96:99], v[40:41], off offset:16
	global_load_dwordx4 v[100:103], v[40:41], off offset:3072
	global_load_dwordx4 v[92:95], v[40:41], off offset:3088
	v_lshl_add_u64 v[44:45], v[44:45], 0, v[142:143]
	v_lshl_add_u64 v[44:45], v[44:45], 0, v[146:147]
	global_load_dwordx4 v[60:63], v[44:45], off
	global_load_dwordx4 v[52:55], v[44:45], off offset:256
	global_load_dwordx4 v[48:51], v[44:45], off offset:512
	s_nop 0
	global_load_dwordx4 v[44:47], v[44:45], off offset:768
	v_mfma_f32_16x16x32_bf16 v[40:43], v[128:131], v[6:9], 0
	v_mfma_f32_16x16x32_bf16 v[88:91], v[120:123], v[2:5], v[40:43]
	s_waitcnt vmcnt(20)
	v_mfma_f32_16x16x32_bf16 v[40:43], v[116:119], v[2:5], v[124:127]
	s_waitcnt lgkmcnt(0)
	s_and_saveexec_b64 s[28:29], s[12:13]
	s_cbranch_execz .LBB0_1147
	v_mov_b32_e32 v0, v184
	s_nop 0
	s_nop 1
	v_add_f32_e32 v151, v88, v0
.LBB0_1147:
	s_or_b64 exec, exec, s[28:29]
	v_mov_b32_e32 v0, 0xff800000
	s_nop 1
	v_mov_b32_e32 v88, 0xff800000
	s_and_saveexec_b64 s[28:29], s[14:15]
	s_cbranch_execz .LBB0_1149
	v_mov_b32_e32 v88, v185
	s_nop 0
	v_add_f32_e32 v88, v89, v88
.LBB0_1149:
	s_or_b64 exec, exec, s[28:29]
	s_and_saveexec_b64 s[28:29], s[16:17]
	s_cbranch_execz .LBB0_1151
	v_mov_b32_e32 v0, v186
	s_nop 0
	v_add_f32_e32 v0, v90, v0
.LBB0_1151:
	s_or_b64 exec, exec, s[28:29]
	v_mov_b32_e32 v89, 0xff800000
	v_mov_b32_e32 v90, 0xff800000
	s_and_saveexec_b64 s[28:29], s[18:19]
	s_cbranch_execz .LBB0_1153
	v_mov_b32_e32 v90, v187
	s_nop 0
	v_add_f32_e32 v90, v91, v90
.LBB0_1153:
	s_or_b64 exec, exec, s[28:29]
	s_and_saveexec_b64 s[28:29], s[20:21]
	s_cbranch_execz .LBB0_1155
	v_mov_b32_e32 v89, v238
	s_nop 0
	v_add_f32_e32 v89, v40, v89
.LBB0_1155:
	s_or_b64 exec, exec, s[28:29]
	v_mov_b32_e32 v40, 0xff800000
	v_mov_b32_e32 v91, 0xff800000
	s_and_saveexec_b64 s[28:29], s[22:23]
	s_cbranch_execz .LBB0_1157
	v_mov_b32_e32 v91, v239
	s_nop 0
	v_add_f32_e32 v91, v41, v91
.LBB0_1157:
	s_or_b64 exec, exec, s[28:29]
	s_and_saveexec_b64 s[28:29], s[24:25]
	s_cbranch_execz .LBB0_1159
	v_mov_b32_e32 v40, v240
	s_nop 0
	v_add_f32_e32 v40, v42, v40
.LBB0_1159:
	s_or_b64 exec, exec, s[28:29]
	v_mov_b32_e32 v116, 0xff800000
	v_mov_b32_e32 v41, 0xff800000
	s_and_saveexec_b64 s[28:29], s[6:7]
	s_cbranch_execz .LBB0_1161
	v_mov_b32_e32 v41, v241
	s_nop 0
	v_add_f32_e32 v41, v43, v41
.LBB0_1161:
	s_or_b64 exec, exec, s[28:29]
	ds_read_b32 v184, v246 offset:1672
	ds_read_b32 v185, v247 offset:1672
	ds_read_b32 v186, v248 offset:1672
	ds_read_b32 v187, v249 offset:1672
	ds_read_b32 v238, v250 offset:1672
	ds_read_b32 v239, v251 offset:1672
	ds_read_b32 v240, v252 offset:1672
	ds_read_b32 v241, v253 offset:1672
	v_max_f32_e32 v42, v88, v88
	v_max_f32_e32 v43, v151, v151
	v_max_f32_e32 v42, v43, v42
	v_max_f32_e32 v43, v90, v90
	v_max_f32_e32 v117, v0, v0
	v_max_f32_e32 v43, v117, v43
	v_max_f32_e32 v117, v41, v41
	v_max_f32_e32 v118, v40, v40
	v_max_f32_e32 v117, v118, v117
	v_max3_f32 v117, v89, v91, v117
	v_max3_f32 v42, v42, v43, v117
	v_mov_b32_e32 v43, v42
	s_nop 1
	v_permlane16_swap_b32_e32 v43, v42
	s_lshl_b32 s1, s0, 6
	s_and_b64 s[2:3], s[26:27], exec
	s_cselect_b32 s2, 2, 0
	v_readlane_b32 s3, v255, 21
	s_waitcnt lgkmcnt(0)
	v_max_f32_e32 v43, v43, v43
	v_max_f32_e32 v42, v42, v43
	v_mov_b32_e32 v43, v42
	s_nop 1
	v_permlane32_swap_b32_e32 v43, v42
	s_or_b32 s26, s2, s3
	s_mul_i32 s44, s26, 0x18000
	s_lshl_b64 s[2:3], s[44:45], 1
	s_add_u32 s2, s42, s2
	s_waitcnt lgkmcnt(0)
	v_max3_f32 v117, v208, v42, v43
	v_sub_f32_e32 v0, v0, v117
	v_mul_f32_e32 v0, 0x3fb8aa3b, v0
	v_exp_f32_e32 v127, v0
	v_sub_f32_e32 v0, v90, v117
	v_mul_f32_e32 v0, 0x3fb8aa3b, v0
	v_exp_f32_e32 v128, v0
	v_sub_f32_e32 v0, v89, v117
	v_sub_f32_e32 v43, v151, v117
	v_mul_f32_e32 v0, 0x3fb8aa3b, v0
	v_mul_f32_e32 v43, 0x3fb8aa3b, v43
	v_exp_f32_e32 v129, v0
	v_sub_f32_e32 v0, v91, v117
	v_exp_f32_e32 v125, v43
	v_sub_f32_e32 v43, v88, v117
	v_mul_f32_e32 v0, 0x3fb8aa3b, v0
	v_sub_f32_e32 v42, v208, v117
	v_mul_f32_e32 v43, 0x3fb8aa3b, v43
	v_exp_f32_e32 v208, v0
	v_sub_f32_e32 v0, v40, v117
	v_exp_f32_e32 v126, v43
	v_mul_f32_e32 v0, 0x3fb8aa3b, v0
	v_exp_f32_e32 v209, v0
	v_sub_f32_e32 v0, v41, v117
	v_mul_f32_e32 v0, 0x3fb8aa3b, v0
	v_mul_f32_e32 v42, 0x3fb8aa3b, v42
	v_exp_f32_e32 v210, v0
	s_addc_u32 s3, s43, s3
	s_lshl_b32 s30, s1, 1
	v_exp_f32_e32 v0, v42
	v_add_u32_e32 v40, 0x8000, v126
	v_add_u32_e32 v41, 0x8000, v125
	s_add_u32 s28, s2, s30
	s_mul_i32 s1, s26, 6
	v_perm_b32 v40, v40, v41, s87
	v_add_u32_e32 v41, 0x8000, v128
	v_add_u32_e32 v42, 0x8000, v127
	s_addc_u32 s29, s3, 0
	s_add_i32 s44, s1, s0
	v_perm_b32 v41, v41, v42, s87
	v_add_u32_e32 v42, 0x8000, v208
	v_add_u32_e32 v43, 0x8000, v129
	s_lshl_b64 s[0:1], s[44:45], 15
	v_perm_b32 v42, v42, v43, s87
	v_add_u32_e32 v43, 0x8000, v210
	v_add_u32_e32 v88, 0x8000, v209
	s_add_u32 s26, s46, s0
	v_mov_b32_e32 v149, v1
	v_perm_b32 v43, v43, v88, s87
	v_pk_mul_f32 v[86:87], v[86:87], v[0:1] op_sel_hi:[1,0]
	v_pk_mul_f32 v[84:85], v[84:85], v[0:1] op_sel_hi:[1,0]
	s_addc_u32 s27, s47, s1
	v_mov_b32_e32 v145, v1
	s_waitcnt vmcnt(19)
	v_mfma_f32_16x16x32_bf16 v[56:59], v[56:59], v[40:43], v[84:87]
	v_mul_f32_e64 v38, v38, v0
	v_mul_f32_e64 v39, v39, v0
	v_pk_mul_f32 v[36:37], v[36:37], v[0:1] op_sel_hi:[1,0]
	v_mov_b32_e32 v143, v1
	v_lshl_add_u64 v[84:85], s[28:29], 0, v[148:149]
	s_waitcnt vmcnt(15)
	v_mfma_f32_16x16x32_bf16 v[112:115], v[112:115], v[6:9], 0
	v_mul_f32_e64 v82, v82, v0
	v_mul_f32_e64 v83, v83, v0
	v_pk_mul_f32 v[80:81], v[80:81], v[0:1] op_sel_hi:[1,0]
	v_pk_mul_f32 v[70:71], v[70:71], v[0:1] op_sel_hi:[1,0]
	v_pk_mul_f32 v[68:69], v[68:69], v[0:1] op_sel_hi:[1,0]
	v_lshl_add_u64 v[130:131], v[84:85], 0, v[144:145]
	v_mfma_f32_16x16x32_bf16 v[12:15], v[12:15], v[40:43], v[36:39]
	v_mov_b32_e32 v147, v1
	s_nop 1
	v_lshl_add_u64 v[36:37], s[26:27], 0, v[142:143]
	v_mfma_f32_16x16x32_bf16 v[20:23], v[20:23], v[40:43], v[80:83]
	v_lshl_add_u64 v[150:151], v[36:37], 0, v[146:147]
	global_load_dwordx4 v[88:91], v[130:131], off
	s_nop 0
	global_load_dwordx4 v[80:83], v[130:131], off offset:16
	v_mfma_f32_16x16x32_bf16 v[16:19], v[16:19], v[40:43], v[68:71]
	global_load_dwordx4 v[84:87], v[130:131], off offset:3072
	s_nop 1
	global_load_dwordx4 v[68:71], v[130:131], off offset:3088
	global_load_dwordx4 v[40:43], v[150:151], off
	global_load_dwordx4 v[36:39], v[150:151], off offset:256
	s_waitcnt vmcnt(19)
	v_mfma_f32_16x16x32_bf16 v[118:121], v[32:35], v[6:9], 0
	v_mfma_f32_16x16x32_bf16 v[112:115], v[28:31], v[2:5], v[112:115]
	global_load_dwordx4 v[32:35], v[150:151], off offset:512
	global_load_dwordx4 v[28:31], v[150:151], off offset:768
	s_waitcnt vmcnt(20)
	v_mfma_f32_16x16x32_bf16 v[104:107], v[104:107], v[2:5], v[118:121]
	s_waitcnt lgkmcnt(0)
	s_and_saveexec_b64 s[34:35], s[12:13]
	s_cbranch_execz .LBB0_1163
	v_mov_b32_e32 v116, v184
	s_nop 0
	v_add_f32_e32 v116, v112, v116
.LBB0_1163:
	s_or_b64 exec, exec, s[34:35]
	s_nop 0
	v_mov_b32_e32 v112, 0xff800000
	v_mov_b32_e32 v118, 0xff800000
	s_and_saveexec_b64 s[34:35], s[14:15]
	s_cbranch_execz .LBB0_1165
	v_mov_b32_e32 v118, v185
	s_nop 0
	v_add_f32_e32 v118, v113, v118
.LBB0_1165:
	s_or_b64 exec, exec, s[34:35]
	s_and_saveexec_b64 s[34:35], s[16:17]
	s_cbranch_execz .LBB0_1167
	v_mov_b32_e32 v112, v186
	s_nop 0
	v_add_f32_e32 v112, v114, v112
.LBB0_1167:
	s_or_b64 exec, exec, s[34:35]
	v_mov_b32_e32 v113, 0xff800000
	v_mov_b32_e32 v114, 0xff800000
	s_and_saveexec_b64 s[34:35], s[18:19]
	s_cbranch_execz .LBB0_1169
	v_mov_b32_e32 v114, v187
	s_nop 0
	v_add_f32_e32 v114, v115, v114
.LBB0_1169:
	s_or_b64 exec, exec, s[34:35]
	s_and_saveexec_b64 s[34:35], s[20:21]
	s_cbranch_execz .LBB0_1171
	v_mov_b32_e32 v113, v238
	s_nop 0
	v_add_f32_e32 v113, v104, v113
.LBB0_1171:
	s_or_b64 exec, exec, s[34:35]
	v_mov_b32_e32 v104, 0xff800000
	v_mov_b32_e32 v115, 0xff800000
	s_and_saveexec_b64 s[34:35], s[22:23]
	s_cbranch_execz .LBB0_1173
	v_mov_b32_e32 v115, v239
	s_nop 0
	v_add_f32_e32 v115, v105, v115
.LBB0_1173:
	s_or_b64 exec, exec, s[34:35]
	s_and_saveexec_b64 s[34:35], s[24:25]
	s_cbranch_execz .LBB0_1175
	v_mov_b32_e32 v104, v240
	s_nop 0
	v_add_f32_e32 v104, v106, v104
.LBB0_1175:
	s_or_b64 exec, exec, s[34:35]
	v_mov_b32_e32 v211, 0xff800000
	v_mov_b32_e32 v105, 0xff800000
	s_and_saveexec_b64 s[34:35], s[6:7]
	s_cbranch_execz .LBB0_1177
	v_mov_b32_e32 v105, v241
	s_nop 0
	v_add_f32_e32 v105, v107, v105
.LBB0_1177:
	s_or_b64 exec, exec, s[34:35]
	ds_read_b32 v184, v246 offset:1796
	ds_read_b32 v185, v247 offset:1796
	ds_read_b32 v186, v248 offset:1796
	ds_read_b32 v187, v249 offset:1796
	ds_read_b32 v238, v250 offset:1796
	ds_read_b32 v239, v251 offset:1796
	ds_read_b32 v240, v252 offset:1796
	ds_read_b32 v241, v253 offset:1796
	v_max_f32_e32 v106, v118, v118
	v_max_f32_e32 v107, v116, v116
	v_max_f32_e32 v106, v107, v106
	v_max_f32_e32 v107, v114, v114
	v_max_f32_e32 v119, v112, v112
	v_max_f32_e32 v107, v119, v107
	v_max_f32_e32 v119, v105, v105
	v_max_f32_e32 v120, v104, v104
	v_max_f32_e32 v119, v120, v119
	v_max3_f32 v119, v113, v115, v119
	v_max3_f32 v106, v106, v107, v119
	v_mov_b32_e32 v107, v106
	s_nop 1
	v_permlane16_swap_b32_e32 v107, v106
	v_mov_b32_e32 v149, v1
	v_mov_b32_e32 v145, v1
	s_mov_b64 s[0:1], 0x6000
	v_mov_b32_e32 v143, v1
	s_waitcnt lgkmcnt(0)
	v_max_f32_e32 v107, v107, v107
	v_max_f32_e32 v106, v106, v107
	v_mov_b32_e32 v107, v106
	s_nop 1
	v_permlane32_swap_b32_e32 v107, v106
	v_mov_b32_e32 v147, v1
	s_waitcnt vmcnt(13)
	v_mfma_f32_16x16x32_bf16 v[100:103], v[100:103], v[6:9], 0
	s_waitcnt lgkmcnt(0)
	v_max3_f32 v212, v117, v106, v107
	v_sub_f32_e32 v107, v116, v212
	v_mul_f32_e32 v107, 0x3fb8aa3b, v107
	v_exp_f32_e32 v213, v107
	v_sub_f32_e32 v107, v118, v212
	v_mul_f32_e32 v107, 0x3fb8aa3b, v107
	v_exp_f32_e32 v214, v107
	v_sub_f32_e32 v107, v112, v212
	v_mul_f32_e32 v107, 0x3fb8aa3b, v107
	v_exp_f32_e32 v215, v107
	v_sub_f32_e32 v107, v114, v212
	v_mul_f32_e32 v107, 0x3fb8aa3b, v107
	v_exp_f32_e32 v216, v107
	v_sub_f32_e32 v107, v113, v212
	v_mul_f32_e32 v107, 0x3fb8aa3b, v107
	v_sub_f32_e32 v104, v104, v212
	v_exp_f32_e32 v217, v107
	v_sub_f32_e32 v107, v115, v212
	v_mul_f32_e32 v104, 0x3fb8aa3b, v104
	v_mul_f32_e32 v107, 0x3fb8aa3b, v107
	v_exp_f32_e32 v219, v104
	v_sub_f32_e32 v104, v105, v212
	v_sub_f32_e32 v106, v117, v212
	v_exp_f32_e32 v218, v107
	v_mul_f32_e32 v104, 0x3fb8aa3b, v104
	v_mul_f32_e32 v106, 0x3fb8aa3b, v106
	v_exp_f32_e32 v220, v104
	v_exp_f32_e32 v124, v106
	v_add_u32_e32 v104, 0x8000, v214
	v_add_u32_e32 v105, 0x8000, v213
	v_perm_b32 v104, v104, v105, s87
	v_add_u32_e32 v105, 0x8000, v216
	v_add_u32_e32 v106, 0x8000, v215
	v_perm_b32 v105, v105, v106, s87
	v_add_u32_e32 v106, 0x8000, v218
	v_add_u32_e32 v107, 0x8000, v217
	v_perm_b32 v106, v106, v107, s87
	v_add_u32_e32 v107, 0x8000, v220
	v_add_u32_e32 v112, 0x8000, v219
	v_perm_b32 v107, v107, v112, s87
	v_pk_mul_f32 v[58:59], v[58:59], v[124:125] op_sel_hi:[1,0]
	v_pk_mul_f32 v[56:57], v[56:57], v[124:125] op_sel_hi:[1,0]
	v_pk_mul_f32 v[22:23], v[22:23], v[124:125] op_sel_hi:[1,0]
	v_pk_mul_f32 v[20:21], v[20:21], v[124:125] op_sel_hi:[1,0]
	v_pk_mul_f32 v[18:19], v[18:19], v[124:125] op_sel_hi:[1,0]
	v_pk_mul_f32 v[16:17], v[16:17], v[124:125] op_sel_hi:[1,0]
	v_pk_mul_f32 v[14:15], v[14:15], v[124:125] op_sel_hi:[1,0]
	v_pk_mul_f32 v[12:13], v[12:13], v[124:125] op_sel_hi:[1,0]
	v_mfma_f32_16x16x32_bf16 v[120:123], v[76:79], v[104:107], v[56:59]
	v_mfma_f32_16x16x32_bf16 v[116:119], v[72:75], v[104:107], v[20:23]
	v_mfma_f32_16x16x32_bf16 v[112:115], v[64:67], v[104:107], v[16:19]
	v_mfma_f32_16x16x32_bf16 v[104:107], v[24:27], v[104:107], v[12:15]
	s_nop 2
	v_lshl_add_u64 v[12:13], s[28:29], 0, v[148:149]
	v_lshl_add_u64 v[12:13], v[12:13], 0, v[144:145]
	v_lshl_add_u64 v[14:15], v[12:13], 0, s[0:1]
	s_movk_i32 s0, 0x6000
	v_add_co_u32_e32 v12, vcc, s0, v12
	s_mov_b64 s[0:1], 0x1000
	s_nop 0
	v_addc_co_u32_e32 v13, vcc, 0, v13, vcc
	global_load_dwordx4 v[64:67], v[14:15], off offset:16
	global_load_dwordx4 v[72:75], v[14:15], off offset:3072
	global_load_dwordx4 v[76:79], v[12:13], off
	global_load_dwordx4 v[56:59], v[14:15], off offset:3088
	v_lshl_add_u64 v[12:13], s[26:27], 0, v[142:143]
	v_lshl_add_u64 v[16:17], v[12:13], 0, v[146:147]
	v_mfma_f32_16x16x32_bf16 v[12:15], v[108:111], v[6:9], 0
	v_lshl_add_u64 v[108:109], v[16:17], 0, s[0:1]
	s_movk_i32 s0, 0x1000
	v_add_co_u32_e32 v24, vcc, s0, v16
	v_mfma_f32_16x16x32_bf16 v[96:99], v[96:99], v[2:5], v[12:15]
	s_nop 0
	v_addc_co_u32_e32 v25, vcc, 0, v17, vcc
	global_load_dwordx4 v[20:23], v[108:109], off offset:256
	global_load_dwordx4 v[16:19], v[108:109], off offset:512
	s_nop 0
	global_load_dwordx4 v[24:27], v[24:25], off
	s_nop 0
	global_load_dwordx4 v[12:15], v[108:109], off offset:768
	s_waitcnt vmcnt(20)
	v_mfma_f32_16x16x32_bf16 v[92:95], v[92:95], v[2:5], v[100:103]
	s_waitcnt lgkmcnt(0)
	s_and_saveexec_b64 s[34:35], s[12:13]
	s_cbranch_execz .LBB0_1179
	s_nop 0
	v_mov_b32_e32 v100, v184
	s_nop 0
	v_add_f32_e32 v211, v96, v100
.LBB0_1179:
	s_or_b64 exec, exec, s[34:35]
	v_mov_b32_e32 v96, 0xff800000
	v_mov_b32_e32 v100, 0xff800000
	s_and_saveexec_b64 s[12:13], s[14:15]
	s_cbranch_execz .LBB0_1181
	v_mov_b32_e32 v100, v185
	s_nop 0
	v_add_f32_e32 v100, v97, v100
.LBB0_1181:
	s_or_b64 exec, exec, s[12:13]
	s_and_saveexec_b64 s[12:13], s[16:17]
	s_cbranch_execz .LBB0_1183
	v_mov_b32_e32 v96, v186
	s_nop 0
	v_add_f32_e32 v96, v98, v96
.LBB0_1183:
	s_or_b64 exec, exec, s[12:13]
	v_mov_b32_e32 v97, 0xff800000
	v_mov_b32_e32 v98, 0xff800000
	s_and_saveexec_b64 s[12:13], s[18:19]
	s_cbranch_execz .LBB0_1185
	v_mov_b32_e32 v98, v187
	s_nop 0
	v_add_f32_e32 v98, v99, v98
.LBB0_1185:
	s_or_b64 exec, exec, s[12:13]
	s_and_saveexec_b64 s[12:13], s[20:21]
	s_cbranch_execz .LBB0_1187
	v_mov_b32_e32 v97, v238
	s_nop 0
	v_add_f32_e32 v97, v92, v97
.LBB0_1187:
	s_or_b64 exec, exec, s[12:13]
	v_mov_b32_e32 v92, 0xff800000
	v_mov_b32_e32 v99, 0xff800000
	s_and_saveexec_b64 s[12:13], s[22:23]
	s_cbranch_execz .LBB0_1192
	v_mov_b32_e32 v99, v239
	s_nop 0
	v_add_f32_e32 v99, v93, v99
	s_or_b64 exec, exec, s[12:13]
	s_and_saveexec_b64 s[12:13], s[24:25]
	s_cbranch_execnz .LBB0_1193

.LBB0_1191:
	v_lshl_add_u32 v54, v189, 2, v151
	v_mov_b32_e32 v54, v239
	s_nop 0
	v_add_f32_e32 v116, v55, v54
	s_or_b64 exec, exec, s[34:35]
	v_mov_b32_e32 v118, 0xff800000
	s_and_saveexec_b64 s[34:35], s[24:25]
	s_cbranch_execnz .LBB0_1108
	s_branch .LBB0_1109

.LBB0_1193:
	v_mov_b32_e32 v92, v240
	s_nop 0
	v_add_f32_e32 v92, v94, v92
	s_or_b64 exec, exec, s[12:13]
	v_mov_b32_e32 v93, 0xff800000
	s_and_saveexec_b64 s[12:13], s[6:7]
	s_cbranch_execz .LBB0_1062
.LBB0_1194:
	v_mov_b32_e32 v93, v241
	s_nop 0
	v_add_f32_e32 v93, v95, v93
	s_branch .LBB0_1062
